# prep2: gain vectors loaded once before the loop (per-trip pointer+gain loads removed); prep2 keeps ds_bpermute exchanges
# speedup vs baseline: 1.0029x; 1.0029x over previous
.LBB0_720:
	s_and_b64 vcc, exec, s[0:1]
	s_cbranch_vccz .LBB0_755
	s_mov_b32 s0, s87
	v_mov_b32_e32 v2, v0
	s_add_u32 s8, s28, 0xf0a0000
	s_addc_u32 s9, s29, 0
	v_lshl_add_u32 v1, s0, 9, v2
	s_mov_b32 s0, 0x200000
	v_cmp_gt_i32_e32 vcc, s0, v1
	s_and_saveexec_b64 s[6:7], vcc
	s_movk_i32 s45, 0xf0
	s_mov_b32 s46, 0x504010c
	s_cbranch_execz .LBB0_736
	s_load_dwordx2 s[4:5], s[30:31], 0x170
	s_load_dword s0, s[20:21], 0x0
	v_and_b32_e32 v4, 7, v2
	v_lshlrev_b32_e32 v16, 3, v4
	v_and_b32_e32 v2, 8, v16
	v_cvt_f32_ubyte0_e32 v5, v2
	v_mul_f32_e32 v6, 0xbf549a78, v5
	s_mov_b32 s3, 0xc2fc0000
	s_waitcnt lgkmcnt(0)
	s_lshl_b32 s2, s0, 9
	v_cmp_gt_f32_e64 s[0:1], s3, v6
	v_mov_b32_e32 v7, 0x42800000
	v_not_b32_e32 v8, 63
	v_cndmask_b32_e64 v6, 0, v7, s[0:1]
	v_fmac_f32_e32 v6, 0xbf549a78, v5
	v_exp_f32_e32 v5, v6
	v_cndmask_b32_e64 v6, 0, v8, s[0:1]
	v_cmp_gt_u32_e32 vcc, 4, v4
	s_mov_b64 s[10:11], 0
	v_ldexp_f32 v17, v5, v6
	v_or_b32_e32 v5, 1, v2
	v_cvt_f32_ubyte0_e32 v5, v5
	v_mul_f32_e32 v6, 0xbf549a78, v5
	v_cmp_gt_f32_e64 s[0:1], s3, v6
	v_lshlrev_b32_e32 v24, 1, v16
	s_nop 0
	v_cndmask_b32_e64 v6, 0, v7, s[0:1]
	v_fmac_f32_e32 v6, 0xbf549a78, v5
	v_exp_f32_e32 v5, v6
	v_cndmask_b32_e64 v6, 0, v8, s[0:1]
	v_ldexp_f32 v37, v5, v6
	v_or_b32_e32 v5, 2, v2
	v_cvt_f32_ubyte0_e32 v5, v5
	v_mul_f32_e32 v6, 0xbf549a78, v5
	v_cmp_gt_f32_e64 s[0:1], s3, v6
	s_nop 1
	v_cndmask_b32_e64 v6, 0, v7, s[0:1]
	v_fmac_f32_e32 v6, 0xbf549a78, v5
	v_exp_f32_e32 v5, v6
	v_cndmask_b32_e64 v6, 0, v8, s[0:1]
	v_ldexp_f32 v42, v5, v6
	v_or_b32_e32 v5, 3, v2
	v_cvt_f32_ubyte0_e32 v5, v5
	v_mul_f32_e32 v6, 0xbf549a78, v5
	v_cmp_gt_f32_e64 s[0:1], s3, v6
	s_nop 1
	v_cndmask_b32_e64 v6, 0, v7, s[0:1]
	v_fmac_f32_e32 v6, 0xbf549a78, v5
	v_exp_f32_e32 v5, v6
	v_cndmask_b32_e64 v6, 0, v8, s[0:1]
	v_ldexp_f32 v43, v5, v6
	v_or_b32_e32 v5, 4, v2
	v_cvt_f32_ubyte0_e32 v5, v5
	v_mul_f32_e32 v6, 0xbf549a78, v5
	v_cmp_gt_f32_e64 s[0:1], s3, v6
	s_nop 1
	v_cndmask_b32_e64 v6, 0, v7, s[0:1]
	v_fmac_f32_e32 v6, 0xbf549a78, v5
	v_exp_f32_e32 v5, v6
	v_cndmask_b32_e64 v6, 0, v8, s[0:1]
	v_ldexp_f32 v44, v5, v6
	v_or_b32_e32 v5, 5, v2
	v_cvt_f32_ubyte0_e32 v5, v5
	v_mul_f32_e32 v6, 0xbf549a78, v5
	v_cmp_gt_f32_e64 s[0:1], s3, v6
	s_nop 1
	v_cndmask_b32_e64 v6, 0, v7, s[0:1]
	v_fmac_f32_e32 v6, 0xbf549a78, v5
	v_exp_f32_e32 v5, v6
	v_cndmask_b32_e64 v6, 0, v8, s[0:1]
	v_ldexp_f32 v45, v5, v6
	v_or_b32_e32 v5, 6, v2
	v_cvt_f32_ubyte0_e32 v5, v5
	v_mul_f32_e32 v6, 0xbf549a78, v5
	v_cmp_gt_f32_e64 s[0:1], s3, v6
	v_or_b32_e32 v2, 7, v2
	v_cvt_f32_ubyte0_e32 v2, v2
	v_cndmask_b32_e64 v6, 0, v7, s[0:1]
	v_fmac_f32_e32 v6, 0xbf549a78, v5
	v_exp_f32_e32 v5, v6
	v_cndmask_b32_e64 v6, 0, v8, s[0:1]
	v_ldexp_f32 v46, v5, v6
	v_mul_f32_e32 v5, 0xbf549a78, v2
	v_cmp_gt_f32_e64 s[0:1], s3, v5
	s_nop 1
	v_cndmask_b32_e64 v5, 0, v7, s[0:1]
	v_fmac_f32_e32 v5, 0xbf549a78, v2
	v_exp_f32_e32 v2, v5
	v_cndmask_b32_e64 v5, 0, v8, s[0:1]
	s_mov_b64 s[0:1], 0x5000000
	v_ldexp_f32 v47, v2, v5
	v_lshlrev_b32_e32 v2, 4, v4
	v_lshlrev_b32_e32 v4, 5, v4
	v_mov_b32_e32 v5, v3
	v_lshl_add_u64 v[4:5], s[4:5], 0, v[4:5]
	v_lshl_add_u64 v[20:21], v[4:5], 0, s[0:1]
	v_and_b32_e32 v4, 64, v223
	v_lshl_add_u64 v[18:19], s[8:9], 0, v[2:3]
	v_lshl_add_u64 v[22:23], s[36:37], 0, v[2:3]
	v_xor_b32_e32 v2, 1, v223
	v_add_u32_e32 v4, 64, v4
	v_cmp_lt_i32_e64 s[0:1], v2, v4
	s_nop 1
	v_cndmask_b32_e64 v2, v223, v2, s[0:1]
	v_lshlrev_b32_e32 v48, 2, v2
	v_xor_b32_e32 v2, 2, v223
	v_cmp_lt_i32_e64 s[0:1], v2, v4
	s_nop 1
	v_cndmask_b32_e64 v2, v223, v2, s[0:1]
	v_lshlrev_b32_e32 v49, 2, v2
	v_xor_b32_e32 v2, 4, v223
	v_cmp_lt_i32_e64 s[0:1], v2, v4
	s_nop 1
	v_cndmask_b32_e64 v2, v223, v2, s[0:1]
	v_lshlrev_b32_e32 v50, 2, v2
	v_mov_b32_e32 v104, 0x100
	global_load_dwordx4 v[100:103], v104, s[30:31]
	v_lshlrev_b32_e32 v106, 2, v16
	v_mov_b32_e32 v107, 0
	s_waitcnt vmcnt(0)
	v_lshl_add_u64 v[100:101], v[100:101], 0, v[106:107]
	v_lshl_add_u64 v[102:103], v[102:103], 0, v[106:107]
	global_load_dwordx4 v[80:83], v[100:101], off
	global_load_dwordx4 v[84:87], v[100:101], off offset:16
	global_load_dwordx4 v[88:91], v[102:103], off
	global_load_dwordx4 v[92:95], v[102:103], off offset:16
	s_waitcnt vmcnt(0)
	s_branch .LBB0_724

.LBB0_724:
	v_ashrrev_i32_e32 v2, 10, v1
	v_bfe_u32 v52, v1, 7, 13
	v_mov_b64_e32 v[4:5], s[34:35]
	v_and_b32_e32 v6, 0xfffffc00, v2
	v_bfe_u32 v51, v1, 3, 4
	v_mad_u64_u32 v[4:5], s[0:1], v52, s67, v[4:5]
	v_ashrrev_i32_e32 v7, 31, v6
	v_lshl_add_u64 v[4:5], v[6:7], 1, v[4:5]
	v_lshlrev_b32_e32 v2, 7, v51
	v_lshl_add_u64 v[4:5], v[4:5], 0, v[2:3]
	v_mov_b32_e32 v25, v3
	v_lshl_add_u64 v[4:5], v[4:5], 0, v[24:25]
	global_load_dwordx4 v[4:7], v[4:5], off
	v_cmp_gt_u32_e64 s[0:1], s43, v1
	s_nop 1
	v_cndmask_b32_e64 v96, v88, v80, s[0:1]
	v_cndmask_b32_e64 v97, v89, v81, s[0:1]
	v_cndmask_b32_e64 v98, v90, v82, s[0:1]
	v_cndmask_b32_e64 v99, v91, v83, s[0:1]
	v_cndmask_b32_e64 v100, v92, v84, s[0:1]
	v_cndmask_b32_e64 v101, v93, v85, s[0:1]
	v_cndmask_b32_e64 v102, v94, v86, s[0:1]
	v_cndmask_b32_e64 v103, v95, v87, s[0:1]
	s_movk_i32 s3, 0x1000
	v_cndmask_b32_e64 v25, 1.0, v232, s[0:1]
	v_cmp_lt_u32_e64 s[0:1], s44, v1
	v_cmp_gt_u32_e64 s[4:5], s3, v52
	s_waitcnt vmcnt(0)
	v_lshlrev_b32_e32 v14, 16, v4
	v_and_b32_e32 v15, 0xffff0000, v4
	v_lshlrev_b32_e32 v32, 16, v5
	v_and_b32_e32 v33, 0xffff0000, v5
	v_pk_mul_f32 v[4:5], v[14:15], v[14:15]
	v_lshlrev_b32_e32 v28, 16, v6
	v_and_b32_e32 v29, 0xffff0000, v6
	v_lshlrev_b32_e32 v12, 16, v7
	v_and_b32_e32 v13, 0xffff0000, v7
	v_pk_mul_f32 v[6:7], v[32:33], v[32:33]
	v_add_f32_e32 v2, v4, v5
	v_add_f32_e32 v2, v2, v6
	v_pk_mul_f32 v[8:9], v[28:29], v[28:29]
	v_add_f32_e32 v2, v7, v2
	v_add_f32_e32 v2, v8, v2
	v_pk_mul_f32 v[10:11], v[12:13], v[12:13]
	v_add_f32_e32 v2, v9, v2
	v_add_f32_e32 v2, v10, v2
	v_add_f32_e32 v30, v11, v2
	v_lshlrev_b32_e32 v2, 2, v16
	s_and_saveexec_b64 s[12:13], s[4:5]
	s_xor_b64 s[12:13], exec, s[12:13]
	s_cbranch_execz .LBB0_726
	v_mov_b64_e32 v[4:5], v[96:97]
	v_mov_b64_e32 v[6:7], v[98:99]
	v_mov_b64_e32 v[8:9], v[100:101]
	v_mov_b64_e32 v[10:11], v[102:103]
	ds_bpermute_b32 v2, v48, v30
	s_waitcnt lgkmcnt(0)
	v_add_f32_e32 v2, v30, v2
	ds_bpermute_b32 v26, v49, v2
	s_waitcnt lgkmcnt(0)
	v_add_f32_e32 v2, v2, v26
	ds_bpermute_b32 v26, v50, v2
	s_waitcnt lgkmcnt(0)
	v_add_f32_e32 v2, v2, v26
	v_fmamk_f32 v2, v2, 0x3c800000, v218
	v_mul_f32_e32 v26, 0x4b800000, v2
	v_cmp_gt_f32_e64 s[4:5], s71, v2
	s_nop 1
	v_cndmask_b32_e64 v2, v2, v26, s[4:5]
	v_rsq_f32_e32 v2, v2
	s_nop 0
	v_mul_f32_e32 v26, 0x45800000, v2
	v_cndmask_b32_e64 v2, v2, v26, s[4:5]
	v_mul_f32_e32 v2, v25, v2
	s_waitcnt vmcnt(1)
	v_pk_mul_f32 v[26:27], v[4:5], v[2:3] op_sel_hi:[1,0]
	v_pk_mul_f32 v[30:31], v[6:7], v[2:3] op_sel_hi:[1,0]
	s_waitcnt vmcnt(0)
	v_pk_mul_f32 v[4:5], v[8:9], v[2:3] op_sel_hi:[1,0]
	v_pk_mul_f32 v[6:7], v[10:11], v[2:3] op_sel_hi:[1,0]
	v_pk_mul_f32 v[4:5], v[4:5], v[28:29]
	v_pk_mul_f32 v[6:7], v[6:7], v[12:13]
	v_pk_mul_f32 v[10:11], v[30:31], v[32:33]
	v_pk_mul_f32 v[8:9], v[26:27], v[14:15]
.LBB0_726:
	s_andn2_saveexec_b64 s[12:13], s[12:13]
	s_cbranch_execz .LBB0_728
	ds_bpermute_b32 v4, v48, v30
	v_lshl_add_u64 v[26:27], v[26:27], 0, v[2:3]
	v_bfe_u32 v2, v1, 7, 6
	s_waitcnt lgkmcnt(0)
	v_add_f32_e32 v4, v30, v4
	ds_bpermute_b32 v5, v49, v4
	s_waitcnt lgkmcnt(0)
	v_add_f32_e32 v4, v4, v5
	ds_bpermute_b32 v5, v50, v4
	s_waitcnt lgkmcnt(0)
	v_add_f32_e32 v4, v4, v5
	v_fmamk_f32 v4, v4, 0x3c800000, v218
	v_cmp_gt_f32_e64 s[4:5], s71, v4
	v_mul_f32_e32 v5, 0x4b800000, v4
	s_nop 0
	v_cndmask_b32_e64 v4, v4, v5, s[4:5]
	v_rsq_f32_e32 v4, v4
	s_nop 0
	v_mul_f32_e32 v5, 0x45800000, v4
	v_cndmask_b32_e64 v4, v4, v5, s[4:5]
	v_mul_f32_e32 v10, v25, v4
	v_bfe_u32 v4, v1, 13, 5
	v_cndmask_b32_e32 v2, v2, v4, vcc
	v_cvt_f32_ubyte0_e32 v2, v2
	v_and_b32_e32 v4, 2, v1
	v_cmp_eq_u32_e64 s[4:5], 0, v4
	v_mul_f32_e32 v4, v17, v2
	v_mul_f32_e32 v4, 0.15915494, v4
	v_cos_f32_e32 v8, v4
	v_sin_f32_e32 v30, v4
	v_mul_f32_e32 v4, v37, v2
	v_mul_f32_e32 v4, 0.15915494, v4
	v_cos_f32_e32 v9, v4
	v_sin_f32_e32 v31, v4
	v_mov_b64_e32 v[4:5], v[100:101]
	v_mov_b64_e32 v[6:7], v[102:103]
	v_mov_b64_e32 v[38:39], v[96:97]
	v_mov_b64_e32 v[40:41], v[98:99]
	s_waitcnt vmcnt(0)
	v_pk_mul_f32 v[26:27], v[38:39], v[10:11] op_sel_hi:[1,0]
	s_nop 0
	v_pk_mul_f32 v[14:15], v[26:27], v[14:15]
	ds_bpermute_b32 v26, v49, v14
	ds_bpermute_b32 v27, v49, v15
	v_mul_f32_e32 v11, v42, v2
	v_mul_f32_e32 v11, 0.15915494, v11
	v_sin_f32_e32 v34, v11
	s_waitcnt lgkmcnt(0)
	v_pk_mul_f32 v[26:27], v[30:31], v[26:27]
	v_cos_f32_e32 v30, v11
	v_mul_f32_e32 v11, v43, v2
	v_mul_f32_e32 v11, 0.15915494, v11
	v_pk_mul_f32 v[38:39], v[40:41], v[10:11] op_sel_hi:[1,0]
	v_sin_f32_e32 v35, v11
	v_pk_mul_f32 v[32:33], v[38:39], v[32:33]
	ds_bpermute_b32 v38, v49, v32
	ds_bpermute_b32 v39, v49, v33
	v_cos_f32_e32 v31, v11
	v_mul_f32_e32 v11, v44, v2
	v_mul_f32_e32 v11, 0.15915494, v11
	v_sin_f32_e32 v40, v11
	s_waitcnt lgkmcnt(0)
	v_pk_mul_f32 v[34:35], v[34:35], v[38:39]
	v_cos_f32_e32 v38, v11
	v_mul_f32_e32 v11, v45, v2
	v_mul_f32_e32 v11, 0.15915494, v11
	v_pk_mul_f32 v[4:5], v[4:5], v[10:11] op_sel_hi:[1,0]
	v_cos_f32_e32 v39, v11
	v_pk_mul_f32 v[4:5], v[4:5], v[28:29]
	ds_bpermute_b32 v28, v49, v4
	ds_bpermute_b32 v29, v49, v5
	v_sin_f32_e32 v41, v11
	v_mul_f32_e32 v11, v46, v2
	v_mul_f32_e32 v11, 0.15915494, v11
	v_pk_mul_f32 v[6:7], v[6:7], v[10:11] op_sel_hi:[1,0]
	v_mul_f32_e32 v2, v47, v2
	v_pk_mul_f32 v[6:7], v[6:7], v[12:13]
	s_waitcnt lgkmcnt(0)
	v_pk_mul_f32 v[28:29], v[40:41], v[28:29]
	v_cos_f32_e32 v40, v11
	v_sin_f32_e32 v54, v11
	v_mul_f32_e32 v2, 0.15915494, v2
	ds_bpermute_b32 v10, v49, v6
	ds_bpermute_b32 v11, v49, v7
	v_sin_f32_e32 v55, v2
	v_cos_f32_e32 v41, v2
	v_cndmask_b32_e64 v27, v27, -v27, s[4:5]
	v_cndmask_b32_e64 v26, v26, -v26, s[4:5]
	s_waitcnt lgkmcnt(0)
	v_pk_mul_f32 v[10:11], v[54:55], v[10:11]
	v_cndmask_b32_e64 v35, v35, -v35, s[4:5]
	v_cndmask_b32_e64 v34, v34, -v34, s[4:5]
	v_cndmask_b32_e64 v29, v29, -v29, s[4:5]
	v_cndmask_b32_e64 v28, v28, -v28, s[4:5]
	v_cndmask_b32_e64 v13, v11, -v11, s[4:5]
	v_cndmask_b32_e64 v12, v10, -v10, s[4:5]
	v_pk_fma_f32 v[8:9], v[8:9], v[14:15], v[26:27]
	v_pk_fma_f32 v[10:11], v[30:31], v[32:33], v[34:35]
	v_pk_fma_f32 v[4:5], v[38:39], v[4:5], v[28:29]
	v_pk_fma_f32 v[6:7], v[40:41], v[6:7], v[12:13]
